# combination on the best version: accumulator zeroing hoisted above the prologue DMA wait + EpiUp halo load issued with the statistics batch + saddr-form K-loop DMAs (each neutral alone), K-loop placem
# speedup vs baseline: 1.0038x; 1.0038x over previous
.LBB0_970:
	s_ashr_i32 s65, s64, 31
	s_lshl_b64 s[78:79], s[64:65], 11
	s_add_u32 s78, s34, s78
	s_addc_u32 s79, s35, s79
	s_and_b64 s[80:81], s[2:3], exec
	s_cselect_b32 s65, s79, s5
	s_cselect_b32 s73, s78, s4
	s_ashr_i32 s67, s66, 31
	s_lshl_b64 s[80:81], s[66:67], 11
	s_add_u32 s80, s40, s80
	s_addc_u32 s81, s41, s81
	s_and_b64 s[82:83], s[2:3], exec
	s_cselect_b32 s67, s81, s7
	s_cselect_b32 s76, s80, s6
	s_add_u32 s4, s4, 0x40080
	s_addc_u32 s5, s5, 0
	s_add_u32 s86, s6, 0x100
	v_mov_b32_e32 v0, 0
	s_addc_u32 s87, s7, 0
	s_mov_b32 s88, -2
	v_mov_b32_e32 v1, 0
	v_mov_b64_e32 v[2:3], 0
	v_mov_b64_e32 v[4:5], 0
	v_mov_b64_e32 v[6:7], 0
	v_mov_b64_e32 v[8:9], 0
	v_mov_b64_e32 v[10:11], 0
	v_mov_b64_e32 v[12:13], 0
	v_mov_b32_e32 v38, 0
	s_nop 0
	s_nop 0
	s_nop 0
	s_nop 0
	s_nop 0
	s_nop 0
	s_nop 0
	s_nop 0
	s_nop 0
	s_nop 0
	s_nop 0
	s_nop 0
	s_nop 0
	s_nop 0

.LBB0_1079:
	s_add_u32 s73, s38, 0x100
	v_mov_b32_e32 v0, 0
	s_addc_u32 s76, s39, 0
	s_mov_b32 s77, -2
	s_waitcnt lgkmcnt(0)
	v_mov_b32_e32 v1, 0
	v_mov_b64_e32 v[2:3], 0
	v_mov_b64_e32 v[4:5], 0
	v_mov_b64_e32 v[6:7], 0
	v_mov_b64_e32 v[8:9], 0
	v_mov_b64_e32 v[36:37], 0
	v_mov_b64_e32 v[38:39], 0
	v_mov_b64_e32 v[40:41], 0
	v_mov_b64_e32 v[42:43], 0
	v_mov_b64_e32 v[44:45], 0
	s_nop 0
	s_nop 0
	s_nop 0
	s_nop 0
	s_nop 0
	s_nop 0
	s_nop 0

.LBB0_1180:
	s_ashr_i32 s37, s36, 31
	s_lshl_b64 s[44:45], s[36:37], 11
	s_add_u32 s44, s34, s44
	s_addc_u32 s45, s35, s45
	s_and_b64 s[52:53], s[0:1], exec
	s_cselect_b32 s37, s45, s3
	s_cselect_b32 s52, s44, s2
	s_ashr_i32 s39, s38, 31
	s_lshl_b64 s[54:55], s[38:39], 11
	s_add_u32 s60, s67, s54
	s_addc_u32 s61, s78, s55
	s_and_b64 s[54:55], s[0:1], exec
	s_cselect_b32 s39, s61, s63
	s_cselect_b32 s53, s60, s62
	s_add_u32 s2, s2, 0x40080
	s_addc_u32 s3, s3, 0
	s_add_u32 s54, s62, 0x100
	v_mov_b32_e32 v0, 0
	s_addc_u32 s55, s63, 0
	s_mov_b32 s56, -2
	v_mov_b32_e32 v1, 0
	v_mov_b64_e32 v[2:3], 0
	v_mov_b64_e32 v[4:5], 0
	v_mov_b64_e32 v[6:7], 0
	v_mov_b64_e32 v[8:9], 0
	v_mov_b64_e32 v[10:11], 0
	v_mov_b64_e32 v[12:13], 0
	v_mov_b32_e32 v14, 0
	v_mov_b64_e32 v[26:27], 0
	s_nop 0
	s_nop 0
	s_nop 0

.LBB0_1881:
	s_add_u32 s56, s24, 0x100
	v_mov_b32_e32 v0, 0
	s_addc_u32 s57, s25, 0
	s_mov_b32 s58, -2
	v_mov_b32_e32 v1, v0
	v_mov_b32_e32 v2, v0
	v_mov_b32_e32 v3, v0
	v_mov_b32_e32 v4, v0
	v_mov_b32_e32 v5, v0
	v_mov_b32_e32 v6, v0
	v_mov_b32_e32 v7, v0
	v_mov_b32_e32 v16, v0
	v_mov_b32_e32 v17, v0
	v_mov_b32_e32 v18, v0
	v_mov_b32_e32 v19, v0
	v_mov_b32_e32 v20, v0
	v_mov_b32_e32 v21, v0
	v_mov_b32_e32 v22, v0
	v_mov_b32_e32 v23, v0
	v_mov_b32_e32 v32, v0
	v_mov_b32_e32 v33, v0
	v_mov_b32_e32 v34, v0
	v_mov_b32_e32 v35, v0
	s_waitcnt vmcnt(0)
	v_mov_b64_e32 v[8:9], 0
	v_mov_b64_e32 v[10:11], 0
	v_mov_b64_e32 v[12:13], 0
	v_mov_b64_e32 v[14:15], 0
	s_nop 0
	s_nop 0
